# previous best + rw_scan loop top toggles the LDS read addresses with one xor each and the tail reuses scalar ops as DPP spacing (eight instructions fewer per 16 steps)
# baseline (speedup 1.0000x reference)
.LBB0_768:
	s_lshl_b32 s0, s8, 5
	s_and_b32 s0, s0, 0xe0
	s_ashr_i32 s11, s8, 3
	s_add_i32 s0, s0, s11
	s_bfe_u32 s9, s0, 0x40003
	s_lshl_b32 s6, s9, 8
	v_lshl_add_u64 v[0:1], v[52:53], 0, s[6:7]
	v_lshl_add_u64 v[4:5], v[54:55], 0, s[6:7]
	global_load_dwordx4 v[0:3], v[0:1], off
	s_bfe_u32 s6, s11, 0x10002
	global_load_dwordx4 v[4:7], v[4:5], off
	s_ashr_i32 s12, s0, 7
	s_cmp_eq_u32 s6, 0
	s_cselect_b64 s[46:47], -1, 0
	s_and_saveexec_b64 s[0:1], s[36:37]
	s_xor_b64 s[0:1], exec, s[0:1]
	v_cndmask_b32_e64 v8, v59, v51, s[46:47]
	s_lshl_b32 s10, s12, 13
	s_lshl_b32 s13, s12, 8
	v_add_u32_e32 v8, s10, v8
	v_mov_b32_e32 v10, s13
	v_mov_b32_e32 v98, s10
	s_or_saveexec_b64 s[0:1], s[0:1]
	s_lshl_b32 s10, s9, 6
	s_xor_b64 exec, exec, s[0:1]
	v_cndmask_b32_e64 v8, v71, v49, s[46:47]
	s_lshl_b32 s13, s12, 8
	v_add_u32_e32 v8, s13, v8
	s_lshl_b32 s12, s12, 13
	v_add_u32_e32 v8, 0x4000, v8
	v_mov_b32_e32 v10, s13
	v_mov_b32_e32 v98, s12
	s_or_b64 exec, exec, s[0:1]
	v_mov_b32_e32 v131, v8
	s_lshl_b32 s0, s6, 5
	s_sub_i32 s0, 16, s0
	v_mov_b32_e32 v132, s0
	v_sub_u32_e32 v133, 0x1fff, v49
	v_cndmask_b32_e64 v133, v133, v49, s[46:47]
	v_add_u32_e32 v133, v98, v133
	s_lshl_b32 s0, s9, 2
	v_mov_b32_e32 v134, s0
	v_lshlrev_b32_e32 v130, 6, v48
	v_lshl_add_u32 v130, v49, 2, v130
	v_add_u32_e32 v130, 0xe810, v130
	s_mul_i32 s6, s6, 0x2100000
	v_ashrrev_i32_e32 v9, 31, v8
	s_add_u32 s24, s86, s6
	v_or_b32_e32 v58, s10, v50
	v_lshlrev_b64 v[12:13], 11, v[8:9]
	s_addc_u32 s25, s87, 0
	v_readlane_b32 s0, v182, 23
	v_lshl_or_b32 v14, v58, 1, v12
	v_mov_b32_e32 v15, v13
	v_readlane_b32 s1, v182, 24
	s_add_u32 s20, s0, s6
	v_lshl_add_u64 v[16:17], s[2:3], 0, v[14:15]
	v_lshl_or_b32 v8, v8, 4, s9
	s_addc_u32 s21, s1, 0
	global_load_dwordx2 v[16:17], v[16:17], off
	v_ashrrev_i32_e32 v9, 31, v8
	v_lshl_add_u64 v[18:19], s[90:91], 0, v[14:15]
	v_lshl_add_u64 v[20:21], s[20:21], 0, v[14:15]
	v_lshl_add_u64 v[14:15], s[24:25], 0, v[14:15]
	v_lshl_add_u64 v[8:9], v[8:9], 2, s[74:75]
	global_load_dwordx2 v[18:19], v[18:19], off
	s_add_u32 vcc_lo, s22, s6
	global_load_dwordx2 v[22:23], v[14:15], off
	v_readlane_b32 s12, v181, 42
	global_load_dword v8, v[8:9], off
	s_addc_u32 vcc_hi, s23, 0
	global_load_dwordx2 v[20:21], v[20:21], off
	s_lshl_b32 s0, s11, 4
	v_readlane_b32 s13, v181, 43
	s_and_b32 s11, s0, 48
	s_lshl_b32 s6, s10, 1
	v_lshl_add_u64 v[12:13], s[12:13], 0, v[12:13]
	v_lshl_add_u64 v[12:13], v[12:13], 0, s[6:7]
	s_lshl_b32 s0, s11, 1
	s_mov_b32 s1, s7
	v_lshl_add_u64 v[12:13], v[12:13], 0, s[0:1]
	v_lshl_add_u64 v[24:25], v[12:13], 0, v[68:69]
	s_add_i32 s10, s10, s11
	s_add_u32 s1, s12, s6
	s_addc_u32 s6, s13, 0
	s_add_u32 s0, s1, s0
	s_addc_u32 s1, s6, 0
	v_lshl_add_u64 v[60:61], s[0:1], 0, v[68:69]
	v_add_u32_e32 v99, 0x4000, v10
	s_mov_b32 s6, 0
	v_mov_b32_e32 v100, v97
	v_mov_b32_e32 v101, v96
	s_waitcnt vmcnt(4)
	v_lshlrev_b32_e32 v26, 16, v16
	v_and_b32_e32 v27, 0xffff0000, v16
	v_pk_mul_f32 v[12:13], v[0:1], v[26:27]
	s_waitcnt vmcnt(2)
	v_alignbit_b32 v11, v23, v22, 16
	s_waitcnt vmcnt(1)
	v_pk_mul_f32 v[30:31], v[12:13], v[8:9] op_sel_hi:[1,0]
	v_alignbit_b32 v9, v17, v16, 16
	v_and_b32_e32 v17, 0xffff0000, v17
	v_and_b32_e32 v16, 0xffff0000, v9
	v_pk_mul_f32 v[14:15], v[2:3], v[16:17]
	v_xor_b32_e32 v13, 0x80000000, v31
	v_pk_mul_f32 v[8:9], v[8:9], v[14:15] op_sel_hi:[0,1]
	v_xor_b32_e32 v12, 0x80000000, v30
	v_xor_b32_e32 v15, 0x80000000, v9
	v_xor_b32_e32 v14, 0x80000000, v8
	ds_write_b128 v81, v[12:15]
	v_lshlrev_b32_e32 v12, 16, v22
	v_and_b32_e32 v13, 0xffff0000, v22
	v_and_b32_e32 v15, 0xffff0000, v23
	v_and_b32_e32 v14, 0xffff0000, v11
	s_waitcnt vmcnt(0)
	v_alignbit_b32 v11, v21, v20, 16
	v_lshlrev_b32_e32 v28, 16, v20
	v_and_b32_e32 v29, 0xffff0000, v20
	v_pk_add_f32 v[12:13], v[12:13], 1.0 op_sel_hi:[1,0] neg_lo:[1,0] neg_hi:[1,0]
	v_pk_add_f32 v[14:15], v[14:15], 1.0 op_sel_hi:[1,0] neg_lo:[1,0] neg_hi:[1,0]
	v_and_b32_e32 v21, 0xffff0000, v21
	v_and_b32_e32 v20, 0xffff0000, v11
	ds_write_b128 v81, v[12:15] offset:256
	v_pk_mul_f32 v[14:15], v[8:9], v[20:21]
	v_pk_add_f32 v[8:9], v[28:29], -1.0 op_sel_hi:[1,0]
	v_pk_mul_f32 v[12:13], v[30:31], v[28:29]
	v_pk_fma_f32 v[8:9], v[4:5], v[8:9], 1.0 op_sel_hi:[1,1,0]
	ds_write_b128 v81, v[12:15] offset:512
	v_pk_mul_f32 v[12:13], v[8:9], v[26:27]
	v_pk_add_f32 v[8:9], v[20:21], -1.0 op_sel_hi:[1,0]
	s_nop 0
	v_pk_fma_f32 v[8:9], v[6:7], v[8:9], 1.0 op_sel_hi:[1,1,0]
	s_nop 0
	v_pk_mul_f32 v[14:15], v[8:9], v[16:17]
	v_alignbit_b32 v8, v19, v18, 16
	ds_write_b128 v81, v[12:15] offset:768
	v_and_b32_e32 v14, 0xffff0000, v8
	global_load_ushort v8, v[24:25], off
	v_and_b32_e32 v15, 0xffff0000, v19
	v_lshlrev_b32_e32 v12, 16, v18
	v_and_b32_e32 v13, 0xffff0000, v18
	ds_write_b128 v81, v[12:15] offset:1024
	s_waitcnt vmcnt(0)
	v_lshlrev_b32_e32 v8, 16, v8
	ds_write_b32 v88, v8 offset:1280
	ds_write_b32 v130, v8
	v_add_u32_e32 v8, s10, v89
	v_ashrrev_i32_e32 v9, 31, v8
	v_lshl_add_u64 v[56:57], v[8:9], 1, vcc
	v_mov_b32_e32 v8, 0
	s_mov_b32 s10, 0
	v_mov_b32_e32 v9, v8
	v_mov_b32_e32 v10, v8
	v_mov_b32_e32 v11, v8
	v_lshlrev_b32_e32 v58, 1, v58
	v_readlane_b32 s100, v181, 42
	v_readlane_b32 s101, v181, 43
	v_sub_u32_e32 v12, 0xff, v48
	v_cndmask_b32_e64 v12, v12, v48, s[46:47]
	v_add_u32_e32 v100, v99, v12
	v_sub_u32_e32 v12, 0x1fff, v48
	v_cndmask_b32_e64 v12, v12, v48, s[46:47]
	v_add_u32_e32 v101, v98, v12
	v_subrev_u32_e32 v60, s100, v60
	v_subrev_u32_e32 v99, s100, v56
	v_lshlrev_b32_e32 v126, 2, v87
	v_add_u32_e32 v126, 0x5410, v126
	v_add_u32_e32 v127, v91, v92
	v_lshlrev_b32_e32 v127, 4, v127
	v_add_u32_e32 v127, 0xec10, v127
	v_add_u32_e32 v131, v132, v131
	v_lshl_add_u32 v13, v131, 11, v58
	v_lshl_add_u32 v14, v131, 6, v134
	v_lshl_add_u32 v15, v131, 11, v60
	global_load_dwordx2 v[74:75], v13, s[2:3]
	global_load_dwordx2 v[62:63], v13, s[90:91]
	global_load_dwordx2 v[76:77], v13, s[24:25]
	global_load_dword v78, v14, s[74:75]
	global_load_dwordx2 v[72:73], v13, s[20:21]
	global_load_ushort v102, v15, s[100:101]
	s_waitcnt lgkmcnt(0)
	s_barrier
	s_branch .LBB0_774
.LBB0_774:
	s_and_b32 s11, s10, 1
	v_xor_b32_e32 v126, 0x5400, v126
	v_xor_b32_e32 v127, 0x400, v127
	ds_read_b128 v[136:139], v127 offset:0
	ds_read_b128 v[184:187], v126 offset:0
	ds_read_b128 v[196:199], v126 offset:768
	ds_read_b128 v[188:191], v126 offset:256
	ds_read_b128 v[200:203], v126 offset:1024
	ds_read_b128 v[192:195], v126 offset:512
	ds_read_b128 v[206:209], v126 offset:1344
	ds_read_b128 v[218:221], v126 offset:2112
	ds_read_b128 v[210:213], v126 offset:1600
	ds_read_b128 v[222:225], v126 offset:2368
	ds_read_b128 v[214:217], v126 offset:1856
	s_waitcnt lgkmcnt(5)
	v_pk_mul_f32 v[250:251], v[8:9], v[184:185]
	v_pk_fma_f32 v[250:251], v[10:11], v[186:187], v[250:251]
	v_add_f32_e32 v14, v250, v251
	v_pk_mul_f32 v[252:253], v[136:137], v[196:197] op_sel_hi:[0,1]
	v_pk_mul_f32 v[254:255], v[136:137], v[198:199] op_sel_hi:[0,1]
	v_add_f32_dpp v14, v14, v14 quad_perm:[1,0,3,2] row_mask:0xf bank_mask:0xf bound_ctrl:1
	v_pk_fma_f32 v[252:253], v[8:9], v[188:189], v[252:253]
	v_pk_fma_f32 v[254:255], v[10:11], v[190:191], v[254:255]
	v_add_f32_dpp v14, v14, v14 quad_perm:[2,3,0,1] row_mask:0xf bank_mask:0xf bound_ctrl:1
	ds_read_b128 v[228:231], v126 offset:2688
	ds_read_b128 v[240:243], v126 offset:3456
	v_add_f32_dpp v14, v14, v14 row_half_mirror row_mask:0xf bank_mask:0xf bound_ctrl:1
	ds_read_b128 v[232:235], v126 offset:2944
	ds_read_b128 v[244:247], v126 offset:3712
	v_add_f32_dpp v14, v14, v14 row_mirror row_mask:0xf bank_mask:0xf bound_ctrl:1
	v_pk_fma_f32 v[10:11], v[14:15], v[194:195], v[254:255] op_sel_hi:[0,1,1]
	v_pk_fma_f32 v[8:9], v[14:15], v[192:193], v[252:253] op_sel_hi:[0,1,1]
	ds_read_b128 v[236:239], v126 offset:3200
	s_waitcnt lgkmcnt(5)
	v_pk_mul_f32 v[250:251], v[8:9], v[206:207]
	v_pk_fma_f32 v[250:251], v[10:11], v[208:209], v[250:251]
	v_add_f32_e32 v14, v250, v251
	v_pk_mul_f32 v[252:253], v[136:137], v[218:219] op_sel:[1,0] op_sel_hi:[1,1]
	v_pk_mul_f32 v[254:255], v[136:137], v[220:221] op_sel:[1,0] op_sel_hi:[1,1]
	v_add_f32_dpp v14, v14, v14 quad_perm:[1,0,3,2] row_mask:0xf bank_mask:0xf bound_ctrl:1
	v_pk_fma_f32 v[252:253], v[8:9], v[210:211], v[252:253]
	v_pk_fma_f32 v[254:255], v[10:11], v[212:213], v[254:255]
	v_add_f32_dpp v14, v14, v14 quad_perm:[2,3,0,1] row_mask:0xf bank_mask:0xf bound_ctrl:1
	v_pk_mul_f32 v[12:13], v[8:9], v[200:201]
	v_pk_fma_f32 v[12:13], v[10:11], v[202:203], v[12:13]
	v_add_f32_dpp v14, v14, v14 row_half_mirror row_mask:0xf bank_mask:0xf bound_ctrl:1
	v_add_f32_e32 v18, v12, v13
	s_nop 0
	v_add_f32_dpp v14, v14, v14 row_mirror row_mask:0xf bank_mask:0xf bound_ctrl:1
	v_pk_fma_f32 v[10:11], v[14:15], v[216:217], v[254:255] op_sel_hi:[0,1,1]
	v_pk_fma_f32 v[8:9], v[14:15], v[214:215], v[252:253] op_sel_hi:[0,1,1]
	ds_read_b128 v[184:187], v126 offset:4032
	ds_read_b128 v[196:199], v126 offset:4800
	ds_read_b128 v[188:191], v126 offset:4288
	ds_read_b128 v[200:203], v126 offset:5056
	ds_read_b128 v[192:195], v126 offset:4544
	s_waitcnt lgkmcnt(5)
	v_pk_mul_f32 v[250:251], v[8:9], v[228:229]
	v_pk_fma_f32 v[250:251], v[10:11], v[230:231], v[250:251]
	v_add_f32_e32 v14, v250, v251
	v_pk_mul_f32 v[252:253], v[138:139], v[240:241] op_sel_hi:[0,1]
	v_pk_mul_f32 v[254:255], v[138:139], v[242:243] op_sel_hi:[0,1]
	v_add_f32_dpp v14, v14, v14 quad_perm:[1,0,3,2] row_mask:0xf bank_mask:0xf bound_ctrl:1
	v_pk_fma_f32 v[252:253], v[8:9], v[232:233], v[252:253]
	v_pk_fma_f32 v[254:255], v[10:11], v[234:235], v[254:255]
	v_add_f32_dpp v14, v14, v14 quad_perm:[2,3,0,1] row_mask:0xf bank_mask:0xf bound_ctrl:1
	v_pk_mul_f32 v[12:13], v[8:9], v[222:223]
	v_pk_fma_f32 v[12:13], v[10:11], v[224:225], v[12:13]
	v_add_f32_dpp v14, v14, v14 row_half_mirror row_mask:0xf bank_mask:0xf bound_ctrl:1
	v_add_f32_e32 v19, v12, v13
	s_nop 0
	v_add_f32_dpp v14, v14, v14 row_mirror row_mask:0xf bank_mask:0xf bound_ctrl:1
	v_pk_fma_f32 v[10:11], v[14:15], v[238:239], v[254:255] op_sel_hi:[0,1,1]
	v_pk_fma_f32 v[8:9], v[14:15], v[236:237], v[252:253] op_sel_hi:[0,1,1]
	ds_read_b128 v[140:143], v127 offset:16
	ds_read_b128 v[206:209], v126 offset:5376
	ds_read_b128 v[218:221], v126 offset:6144
	ds_read_b128 v[210:213], v126 offset:5632
	ds_read_b128 v[222:225], v126 offset:6400
	ds_read_b128 v[214:217], v126 offset:5888
	s_waitcnt lgkmcnt(6)
	v_pk_mul_f32 v[250:251], v[8:9], v[184:185]
	v_pk_fma_f32 v[250:251], v[10:11], v[186:187], v[250:251]
	v_add_f32_e32 v14, v250, v251
	v_pk_mul_f32 v[252:253], v[138:139], v[196:197] op_sel:[1,0] op_sel_hi:[1,1]
	v_pk_mul_f32 v[254:255], v[138:139], v[198:199] op_sel:[1,0] op_sel_hi:[1,1]
	v_add_f32_dpp v14, v14, v14 quad_perm:[1,0,3,2] row_mask:0xf bank_mask:0xf bound_ctrl:1
	v_pk_fma_f32 v[252:253], v[8:9], v[188:189], v[252:253]
	v_pk_fma_f32 v[254:255], v[10:11], v[190:191], v[254:255]
	v_add_f32_dpp v14, v14, v14 quad_perm:[2,3,0,1] row_mask:0xf bank_mask:0xf bound_ctrl:1
	v_pk_mul_f32 v[12:13], v[8:9], v[244:245]
	v_pk_fma_f32 v[12:13], v[10:11], v[246:247], v[12:13]
	v_add_f32_dpp v14, v14, v14 row_half_mirror row_mask:0xf bank_mask:0xf bound_ctrl:1
	v_add_f32_e32 v20, v12, v13
	s_nop 0
	v_add_f32_dpp v14, v14, v14 row_mirror row_mask:0xf bank_mask:0xf bound_ctrl:1
	v_pk_fma_f32 v[10:11], v[14:15], v[194:195], v[254:255] op_sel_hi:[0,1,1]
	v_pk_fma_f32 v[8:9], v[14:15], v[192:193], v[252:253] op_sel_hi:[0,1,1]
	ds_read_b128 v[228:231], v126 offset:6720
	ds_read_b128 v[240:243], v126 offset:7488
	ds_read_b128 v[232:235], v126 offset:6976
	ds_read_b128 v[244:247], v126 offset:7744
	ds_read_b128 v[236:239], v126 offset:7232
	s_waitcnt lgkmcnt(5)
	v_pk_mul_f32 v[250:251], v[8:9], v[206:207]
	v_pk_fma_f32 v[250:251], v[10:11], v[208:209], v[250:251]
	v_add_f32_e32 v14, v250, v251
	v_pk_mul_f32 v[252:253], v[140:141], v[218:219] op_sel_hi:[0,1]
	v_pk_mul_f32 v[254:255], v[140:141], v[220:221] op_sel_hi:[0,1]
	v_add_f32_dpp v14, v14, v14 quad_perm:[1,0,3,2] row_mask:0xf bank_mask:0xf bound_ctrl:1
	v_pk_fma_f32 v[252:253], v[8:9], v[210:211], v[252:253]
	v_pk_fma_f32 v[254:255], v[10:11], v[212:213], v[254:255]
	v_add_f32_dpp v14, v14, v14 quad_perm:[2,3,0,1] row_mask:0xf bank_mask:0xf bound_ctrl:1
	v_pk_mul_f32 v[12:13], v[8:9], v[200:201]
	v_pk_fma_f32 v[12:13], v[10:11], v[202:203], v[12:13]
	v_add_f32_dpp v14, v14, v14 row_half_mirror row_mask:0xf bank_mask:0xf bound_ctrl:1
	v_add_f32_e32 v21, v12, v13
	s_nop 0
	v_add_f32_dpp v14, v14, v14 row_mirror row_mask:0xf bank_mask:0xf bound_ctrl:1
	v_pk_fma_f32 v[10:11], v[14:15], v[216:217], v[254:255] op_sel_hi:[0,1,1]
	v_pk_fma_f32 v[8:9], v[14:15], v[214:215], v[252:253] op_sel_hi:[0,1,1]
	ds_read_b128 v[184:187], v126 offset:8064
	ds_read_b128 v[196:199], v126 offset:8832
	ds_read_b128 v[188:191], v126 offset:8320
	ds_read_b128 v[200:203], v126 offset:9088
	ds_read_b128 v[192:195], v126 offset:8576
	s_waitcnt lgkmcnt(5)
	v_pk_mul_f32 v[250:251], v[8:9], v[228:229]
	v_pk_fma_f32 v[250:251], v[10:11], v[230:231], v[250:251]
	v_add_f32_e32 v14, v250, v251
	v_pk_mul_f32 v[252:253], v[140:141], v[240:241] op_sel:[1,0] op_sel_hi:[1,1]
	v_pk_mul_f32 v[254:255], v[140:141], v[242:243] op_sel:[1,0] op_sel_hi:[1,1]
	v_add_f32_dpp v14, v14, v14 quad_perm:[1,0,3,2] row_mask:0xf bank_mask:0xf bound_ctrl:1
	v_pk_fma_f32 v[252:253], v[8:9], v[232:233], v[252:253]
	v_pk_fma_f32 v[254:255], v[10:11], v[234:235], v[254:255]
	v_add_f32_dpp v14, v14, v14 quad_perm:[2,3,0,1] row_mask:0xf bank_mask:0xf bound_ctrl:1
	v_pk_mul_f32 v[12:13], v[8:9], v[222:223]
	v_pk_fma_f32 v[12:13], v[10:11], v[224:225], v[12:13]
	v_add_f32_dpp v14, v14, v14 row_half_mirror row_mask:0xf bank_mask:0xf bound_ctrl:1
	v_add_f32_e32 v22, v12, v13
	s_nop 0
	v_add_f32_dpp v14, v14, v14 row_mirror row_mask:0xf bank_mask:0xf bound_ctrl:1
	v_pk_fma_f32 v[10:11], v[14:15], v[238:239], v[254:255] op_sel_hi:[0,1,1]
	v_pk_fma_f32 v[8:9], v[14:15], v[236:237], v[252:253] op_sel_hi:[0,1,1]
	ds_read_b128 v[206:209], v126 offset:9408
	ds_read_b128 v[218:221], v126 offset:10176
	ds_read_b128 v[210:213], v126 offset:9664
	ds_read_b128 v[222:225], v126 offset:10432
	ds_read_b128 v[214:217], v126 offset:9920
	s_waitcnt lgkmcnt(5)
	v_pk_mul_f32 v[250:251], v[8:9], v[184:185]
	v_pk_fma_f32 v[250:251], v[10:11], v[186:187], v[250:251]
	v_add_f32_e32 v14, v250, v251
	v_pk_mul_f32 v[252:253], v[142:143], v[196:197] op_sel_hi:[0,1]
	v_pk_mul_f32 v[254:255], v[142:143], v[198:199] op_sel_hi:[0,1]
	v_add_f32_dpp v14, v14, v14 quad_perm:[1,0,3,2] row_mask:0xf bank_mask:0xf bound_ctrl:1
	v_pk_fma_f32 v[252:253], v[8:9], v[188:189], v[252:253]
	v_pk_fma_f32 v[254:255], v[10:11], v[190:191], v[254:255]
	v_add_f32_dpp v14, v14, v14 quad_perm:[2,3,0,1] row_mask:0xf bank_mask:0xf bound_ctrl:1
	v_pk_mul_f32 v[12:13], v[8:9], v[244:245]
	v_pk_fma_f32 v[12:13], v[10:11], v[246:247], v[12:13]
	v_add_f32_dpp v14, v14, v14 row_half_mirror row_mask:0xf bank_mask:0xf bound_ctrl:1
	v_add_f32_e32 v23, v12, v13
	s_nop 0
	v_add_f32_dpp v14, v14, v14 row_mirror row_mask:0xf bank_mask:0xf bound_ctrl:1
	v_pk_fma_f32 v[10:11], v[14:15], v[194:195], v[254:255] op_sel_hi:[0,1,1]
	v_pk_fma_f32 v[8:9], v[14:15], v[192:193], v[252:253] op_sel_hi:[0,1,1]
	ds_read_b128 v[136:139], v127 offset:32
	ds_read_b128 v[228:231], v126 offset:10752
	ds_read_b128 v[240:243], v126 offset:11520
	ds_read_b128 v[232:235], v126 offset:11008
	ds_read_b128 v[244:247], v126 offset:11776
	ds_read_b128 v[236:239], v126 offset:11264
	s_waitcnt lgkmcnt(6)
	v_pk_mul_f32 v[250:251], v[8:9], v[206:207]
	v_pk_fma_f32 v[250:251], v[10:11], v[208:209], v[250:251]
	v_add_f32_e32 v14, v250, v251
	v_pk_mul_f32 v[252:253], v[142:143], v[218:219] op_sel:[1,0] op_sel_hi:[1,1]
	v_pk_mul_f32 v[254:255], v[142:143], v[220:221] op_sel:[1,0] op_sel_hi:[1,1]
	v_add_f32_dpp v14, v14, v14 quad_perm:[1,0,3,2] row_mask:0xf bank_mask:0xf bound_ctrl:1
	v_pk_fma_f32 v[252:253], v[8:9], v[210:211], v[252:253]
	v_pk_fma_f32 v[254:255], v[10:11], v[212:213], v[254:255]
	v_add_f32_dpp v14, v14, v14 quad_perm:[2,3,0,1] row_mask:0xf bank_mask:0xf bound_ctrl:1
	v_pk_mul_f32 v[12:13], v[8:9], v[200:201]
	v_pk_fma_f32 v[12:13], v[10:11], v[202:203], v[12:13]
	v_add_f32_dpp v14, v14, v14 row_half_mirror row_mask:0xf bank_mask:0xf bound_ctrl:1
	v_add_f32_e32 v24, v12, v13
	s_nop 0
	v_add_f32_dpp v14, v14, v14 row_mirror row_mask:0xf bank_mask:0xf bound_ctrl:1
	v_pk_fma_f32 v[10:11], v[14:15], v[216:217], v[254:255] op_sel_hi:[0,1,1]
	v_pk_fma_f32 v[8:9], v[14:15], v[214:215], v[252:253] op_sel_hi:[0,1,1]
	ds_read_b128 v[184:187], v126 offset:12096
	ds_read_b128 v[196:199], v126 offset:12864
	ds_read_b128 v[188:191], v126 offset:12352
	ds_read_b128 v[200:203], v126 offset:13120
	ds_read_b128 v[192:195], v126 offset:12608
	s_waitcnt lgkmcnt(5)
	v_pk_mul_f32 v[250:251], v[8:9], v[228:229]
	v_pk_fma_f32 v[250:251], v[10:11], v[230:231], v[250:251]
	v_add_f32_e32 v14, v250, v251
	v_pk_mul_f32 v[252:253], v[136:137], v[240:241] op_sel_hi:[0,1]
	v_pk_mul_f32 v[254:255], v[136:137], v[242:243] op_sel_hi:[0,1]
	v_add_f32_dpp v14, v14, v14 quad_perm:[1,0,3,2] row_mask:0xf bank_mask:0xf bound_ctrl:1
	v_pk_fma_f32 v[252:253], v[8:9], v[232:233], v[252:253]
	v_pk_fma_f32 v[254:255], v[10:11], v[234:235], v[254:255]
	v_add_f32_dpp v14, v14, v14 quad_perm:[2,3,0,1] row_mask:0xf bank_mask:0xf bound_ctrl:1
	v_pk_mul_f32 v[12:13], v[8:9], v[222:223]
	v_pk_fma_f32 v[12:13], v[10:11], v[224:225], v[12:13]
	v_add_f32_dpp v14, v14, v14 row_half_mirror row_mask:0xf bank_mask:0xf bound_ctrl:1
	v_add_f32_e32 v25, v12, v13
	s_nop 0
	v_add_f32_dpp v14, v14, v14 row_mirror row_mask:0xf bank_mask:0xf bound_ctrl:1
	v_pk_fma_f32 v[10:11], v[14:15], v[238:239], v[254:255] op_sel_hi:[0,1,1]
	v_pk_fma_f32 v[8:9], v[14:15], v[236:237], v[252:253] op_sel_hi:[0,1,1]
	ds_read_b128 v[206:209], v126 offset:13440
	ds_read_b128 v[218:221], v126 offset:14208
	ds_read_b128 v[210:213], v126 offset:13696
	ds_read_b128 v[222:225], v126 offset:14464
	ds_read_b128 v[214:217], v126 offset:13952
	s_waitcnt vmcnt(0)
	s_xor_b32 s0, s11, 1
	v_lshl_add_u32 v170, s0, 10, v130
	s_mulk_i32 s0, 0x5400
	v_add_u32_e32 v82, s0, v79
	v_lshlrev_b32_e32 v34, 16, v74
	v_and_b32_e32 v35, 0xffff0000, v74
	v_lshlrev_b32_e32 v36, 16, v75
	v_and_b32_e32 v37, 0xffff0000, v75
	v_lshl_add_u32 v83, v50, 2, v82
	v_pk_mul_f32 v[38:39], v[0:1], v[34:35]
	v_pk_mul_f32 v[40:41], v[2:3], v[36:37]
	v_lshlrev_b32_e32 v120, 16, v72
	v_pk_mul_f32 v[42:43], v[78:79], v[38:39] op_sel_hi:[0,1] neg_lo:[1,0] neg_hi:[1,0]
	v_pk_mul_f32 v[44:45], v[78:79], v[40:41] op_sel_hi:[0,1] neg_lo:[1,0] neg_hi:[1,0]
	v_and_b32_e32 v121, 0xffff0000, v72
	v_lshlrev_b32_e32 v122, 16, v73
	v_and_b32_e32 v123, 0xffff0000, v73
	ds_write_b128 v83, v[42:45]
	v_lshlrev_b32_e32 v38, 16, v76
	v_and_b32_e32 v39, 0xffff0000, v76
	v_lshlrev_b32_e32 v40, 16, v77
	v_and_b32_e32 v41, 0xffff0000, v77
	v_pk_add_f32 v[38:39], v[38:39], 1.0 op_sel_hi:[1,0] neg_lo:[1,0] neg_hi:[1,0]
	v_pk_add_f32 v[40:41], v[40:41], 1.0 op_sel_hi:[1,0] neg_lo:[1,0] neg_hi:[1,0]
	v_lshl_add_u32 v85, v48, 2, v82
	ds_write_b128 v83, v[38:41] offset:256
	v_pk_mul_f32 v[38:39], v[42:43], v[120:121] neg_lo:[1,0] neg_hi:[1,0]
	v_pk_mul_f32 v[40:41], v[44:45], v[122:123] neg_lo:[1,0] neg_hi:[1,0]
	v_pk_add_f32 v[120:121], v[120:121], -1.0 op_sel_hi:[1,0]
	v_pk_add_f32 v[122:123], v[122:123], -1.0 op_sel_hi:[1,0]
	ds_write_b128 v83, v[38:41] offset:512
	v_pk_fma_f32 v[120:121], v[4:5], v[120:121], 1.0 op_sel_hi:[1,1,0]
	v_pk_fma_f32 v[122:123], v[6:7], v[122:123], 1.0 op_sel_hi:[1,1,0]
	v_lshlrev_b32_e32 v42, 16, v62
	v_and_b32_e32 v43, 0xffff0000, v62
	v_pk_mul_f32 v[120:121], v[120:121], v[34:35]
	v_pk_mul_f32 v[122:123], v[122:123], v[36:37]
	v_lshlrev_b32_e32 v44, 16, v63
	v_and_b32_e32 v45, 0xffff0000, v63
	v_lshlrev_b32_e32 v84, 16, v102
	ds_write_b128 v83, v[120:123] offset:768
	ds_write_b128 v83, v[42:45] offset:1024
	ds_write_b32 v85, v84 offset:1280
	ds_write_b32 v170, v84
	s_cmpk_eq_i32 s6, 0x20e0
	s_cbranch_scc1 .Lscan_pf_skip
	v_add_u32_e32 v131, v132, v131
	s_cmp_eq_u32 s10, 14
	s_cbranch_scc0 .Lscan_pf_nox
	v_mov_b32_e32 v131, v133

.Lscan_pf_skip:
	s_waitcnt lgkmcnt(12)
	v_pk_mul_f32 v[250:251], v[8:9], v[184:185]
	v_pk_fma_f32 v[250:251], v[10:11], v[186:187], v[250:251]
	v_add_f32_e32 v14, v250, v251
	v_pk_mul_f32 v[252:253], v[136:137], v[196:197] op_sel:[1,0] op_sel_hi:[1,1]
	v_pk_mul_f32 v[254:255], v[136:137], v[198:199] op_sel:[1,0] op_sel_hi:[1,1]
	v_add_f32_dpp v14, v14, v14 quad_perm:[1,0,3,2] row_mask:0xf bank_mask:0xf bound_ctrl:1
	v_pk_fma_f32 v[252:253], v[8:9], v[188:189], v[252:253]
	v_pk_fma_f32 v[254:255], v[10:11], v[190:191], v[254:255]
	v_add_f32_dpp v14, v14, v14 quad_perm:[2,3,0,1] row_mask:0xf bank_mask:0xf bound_ctrl:1
	v_pk_mul_f32 v[12:13], v[8:9], v[244:245]
	v_pk_fma_f32 v[12:13], v[10:11], v[246:247], v[12:13]
	v_add_f32_dpp v14, v14, v14 row_half_mirror row_mask:0xf bank_mask:0xf bound_ctrl:1
	v_add_f32_e32 v26, v12, v13
	s_nop 0
	v_add_f32_dpp v14, v14, v14 row_mirror row_mask:0xf bank_mask:0xf bound_ctrl:1
	v_pk_fma_f32 v[10:11], v[14:15], v[194:195], v[254:255] op_sel_hi:[0,1,1]
	v_pk_fma_f32 v[8:9], v[14:15], v[192:193], v[252:253] op_sel_hi:[0,1,1]
	ds_read_b128 v[228:231], v126 offset:14784
	ds_read_b128 v[240:243], v126 offset:15552
	ds_read_b128 v[232:235], v126 offset:15040
	ds_read_b128 v[244:247], v126 offset:15808
	ds_read_b128 v[236:239], v126 offset:15296
	s_waitcnt lgkmcnt(12)
	v_pk_mul_f32 v[250:251], v[8:9], v[206:207]
	v_pk_fma_f32 v[250:251], v[10:11], v[208:209], v[250:251]
	v_add_f32_e32 v14, v250, v251
	v_pk_mul_f32 v[252:253], v[138:139], v[218:219] op_sel_hi:[0,1]
	v_pk_mul_f32 v[254:255], v[138:139], v[220:221] op_sel_hi:[0,1]
	v_add_f32_dpp v14, v14, v14 quad_perm:[1,0,3,2] row_mask:0xf bank_mask:0xf bound_ctrl:1
	v_pk_fma_f32 v[252:253], v[8:9], v[210:211], v[252:253]
	v_pk_fma_f32 v[254:255], v[10:11], v[212:213], v[254:255]
	v_add_f32_dpp v14, v14, v14 quad_perm:[2,3,0,1] row_mask:0xf bank_mask:0xf bound_ctrl:1
	v_pk_mul_f32 v[12:13], v[8:9], v[200:201]
	v_pk_fma_f32 v[12:13], v[10:11], v[202:203], v[12:13]
	v_add_f32_dpp v14, v14, v14 row_half_mirror row_mask:0xf bank_mask:0xf bound_ctrl:1
	v_add_f32_e32 v27, v12, v13
	s_nop 0
	v_add_f32_dpp v14, v14, v14 row_mirror row_mask:0xf bank_mask:0xf bound_ctrl:1
	v_pk_fma_f32 v[10:11], v[14:15], v[216:217], v[254:255] op_sel_hi:[0,1,1]
	v_pk_fma_f32 v[8:9], v[14:15], v[214:215], v[252:253] op_sel_hi:[0,1,1]
	ds_read_b128 v[140:143], v127 offset:48
	ds_read_b128 v[184:187], v126 offset:16128
	ds_read_b128 v[196:199], v126 offset:16896
	ds_read_b128 v[188:191], v126 offset:16384
	ds_read_b128 v[200:203], v126 offset:17152
	ds_read_b128 v[192:195], v126 offset:16640
	s_waitcnt lgkmcnt(6)
	v_pk_mul_f32 v[250:251], v[8:9], v[228:229]
	v_pk_fma_f32 v[250:251], v[10:11], v[230:231], v[250:251]
	v_add_f32_e32 v14, v250, v251
	v_pk_mul_f32 v[252:253], v[138:139], v[240:241] op_sel:[1,0] op_sel_hi:[1,1]
	v_pk_mul_f32 v[254:255], v[138:139], v[242:243] op_sel:[1,0] op_sel_hi:[1,1]
	v_add_f32_dpp v14, v14, v14 quad_perm:[1,0,3,2] row_mask:0xf bank_mask:0xf bound_ctrl:1
	v_pk_fma_f32 v[252:253], v[8:9], v[232:233], v[252:253]
	v_pk_fma_f32 v[254:255], v[10:11], v[234:235], v[254:255]
	v_add_f32_dpp v14, v14, v14 quad_perm:[2,3,0,1] row_mask:0xf bank_mask:0xf bound_ctrl:1
	v_pk_mul_f32 v[12:13], v[8:9], v[222:223]
	v_pk_fma_f32 v[12:13], v[10:11], v[224:225], v[12:13]
	v_add_f32_dpp v14, v14, v14 row_half_mirror row_mask:0xf bank_mask:0xf bound_ctrl:1
	v_add_f32_e32 v28, v12, v13
	s_nop 0
	v_add_f32_dpp v14, v14, v14 row_mirror row_mask:0xf bank_mask:0xf bound_ctrl:1
	v_pk_fma_f32 v[10:11], v[14:15], v[238:239], v[254:255] op_sel_hi:[0,1,1]
	v_pk_fma_f32 v[8:9], v[14:15], v[236:237], v[252:253] op_sel_hi:[0,1,1]
	ds_read_b128 v[206:209], v126 offset:17472
	ds_read_b128 v[218:221], v126 offset:18240
	ds_read_b128 v[210:213], v126 offset:17728
	ds_read_b128 v[222:225], v126 offset:18496
	ds_read_b128 v[214:217], v126 offset:17984
	s_waitcnt lgkmcnt(5)
	v_pk_mul_f32 v[250:251], v[8:9], v[184:185]
	v_pk_fma_f32 v[250:251], v[10:11], v[186:187], v[250:251]
	v_add_f32_e32 v14, v250, v251
	v_pk_mul_f32 v[252:253], v[140:141], v[196:197] op_sel_hi:[0,1]
	v_pk_mul_f32 v[254:255], v[140:141], v[198:199] op_sel_hi:[0,1]
	v_add_f32_dpp v14, v14, v14 quad_perm:[1,0,3,2] row_mask:0xf bank_mask:0xf bound_ctrl:1
	v_pk_fma_f32 v[252:253], v[8:9], v[188:189], v[252:253]
	v_pk_fma_f32 v[254:255], v[10:11], v[190:191], v[254:255]
	v_add_f32_dpp v14, v14, v14 quad_perm:[2,3,0,1] row_mask:0xf bank_mask:0xf bound_ctrl:1
	v_pk_mul_f32 v[12:13], v[8:9], v[244:245]
	v_pk_fma_f32 v[12:13], v[10:11], v[246:247], v[12:13]
	v_add_f32_dpp v14, v14, v14 row_half_mirror row_mask:0xf bank_mask:0xf bound_ctrl:1
	v_add_f32_e32 v29, v12, v13
	s_nop 0
	v_add_f32_dpp v14, v14, v14 row_mirror row_mask:0xf bank_mask:0xf bound_ctrl:1
	v_pk_fma_f32 v[10:11], v[14:15], v[194:195], v[254:255] op_sel_hi:[0,1,1]
	v_pk_fma_f32 v[8:9], v[14:15], v[192:193], v[252:253] op_sel_hi:[0,1,1]
	ds_read_b128 v[228:231], v126 offset:18816
	ds_read_b128 v[240:243], v126 offset:19584
	ds_read_b128 v[232:235], v126 offset:19072
	ds_read_b128 v[244:247], v126 offset:19840
	ds_read_b128 v[236:239], v126 offset:19328
	s_waitcnt lgkmcnt(5)
	v_pk_mul_f32 v[250:251], v[8:9], v[206:207]
	v_pk_fma_f32 v[250:251], v[10:11], v[208:209], v[250:251]
	v_add_f32_e32 v14, v250, v251
	v_pk_mul_f32 v[252:253], v[140:141], v[218:219] op_sel:[1,0] op_sel_hi:[1,1]
	v_pk_mul_f32 v[254:255], v[140:141], v[220:221] op_sel:[1,0] op_sel_hi:[1,1]
	v_add_f32_dpp v14, v14, v14 quad_perm:[1,0,3,2] row_mask:0xf bank_mask:0xf bound_ctrl:1
	v_pk_fma_f32 v[252:253], v[8:9], v[210:211], v[252:253]
	v_pk_fma_f32 v[254:255], v[10:11], v[212:213], v[254:255]
	v_add_f32_dpp v14, v14, v14 quad_perm:[2,3,0,1] row_mask:0xf bank_mask:0xf bound_ctrl:1
	v_pk_mul_f32 v[12:13], v[8:9], v[200:201]
	v_pk_fma_f32 v[12:13], v[10:11], v[202:203], v[12:13]
	v_add_f32_dpp v14, v14, v14 row_half_mirror row_mask:0xf bank_mask:0xf bound_ctrl:1
	v_add_f32_e32 v30, v12, v13
	s_nop 0
	v_add_f32_dpp v14, v14, v14 row_mirror row_mask:0xf bank_mask:0xf bound_ctrl:1
	v_pk_fma_f32 v[10:11], v[14:15], v[216:217], v[254:255] op_sel_hi:[0,1,1]
	v_pk_fma_f32 v[8:9], v[14:15], v[214:215], v[252:253] op_sel_hi:[0,1,1]
	ds_read_b128 v[184:187], v126 offset:20160
	ds_read_b128 v[196:199], v126 offset:20928
	ds_read_b128 v[188:191], v126 offset:20416
	ds_read_b128 v[200:203], v126 offset:21184
	ds_read_b128 v[192:195], v126 offset:20672
	s_waitcnt lgkmcnt(5)
	v_pk_mul_f32 v[250:251], v[8:9], v[228:229]
	v_pk_fma_f32 v[250:251], v[10:11], v[230:231], v[250:251]
	v_add_f32_e32 v14, v250, v251
	v_pk_mul_f32 v[252:253], v[142:143], v[240:241] op_sel_hi:[0,1]
	v_pk_mul_f32 v[254:255], v[142:143], v[242:243] op_sel_hi:[0,1]
	v_add_f32_dpp v14, v14, v14 quad_perm:[1,0,3,2] row_mask:0xf bank_mask:0xf bound_ctrl:1
	v_pk_fma_f32 v[252:253], v[8:9], v[232:233], v[252:253]
	v_pk_fma_f32 v[254:255], v[10:11], v[234:235], v[254:255]
	v_add_f32_dpp v14, v14, v14 quad_perm:[2,3,0,1] row_mask:0xf bank_mask:0xf bound_ctrl:1
	v_pk_mul_f32 v[12:13], v[8:9], v[222:223]
	v_pk_fma_f32 v[12:13], v[10:11], v[224:225], v[12:13]
	v_add_f32_dpp v14, v14, v14 row_half_mirror row_mask:0xf bank_mask:0xf bound_ctrl:1
	v_add_f32_e32 v31, v12, v13
	s_nop 0
	v_add_f32_dpp v14, v14, v14 row_mirror row_mask:0xf bank_mask:0xf bound_ctrl:1
	v_pk_fma_f32 v[10:11], v[14:15], v[238:239], v[254:255] op_sel_hi:[0,1,1]
	v_pk_fma_f32 v[8:9], v[14:15], v[236:237], v[252:253] op_sel_hi:[0,1,1]
	s_waitcnt lgkmcnt(0)
	v_pk_mul_f32 v[250:251], v[8:9], v[184:185]
	v_pk_fma_f32 v[250:251], v[10:11], v[186:187], v[250:251]
	v_add_f32_e32 v14, v250, v251
	v_pk_mul_f32 v[252:253], v[142:143], v[196:197] op_sel:[1,0] op_sel_hi:[1,1]
	v_pk_mul_f32 v[254:255], v[142:143], v[198:199] op_sel:[1,0] op_sel_hi:[1,1]
	v_add_f32_dpp v14, v14, v14 quad_perm:[1,0,3,2] row_mask:0xf bank_mask:0xf bound_ctrl:1
	v_pk_fma_f32 v[252:253], v[8:9], v[188:189], v[252:253]
	v_pk_fma_f32 v[254:255], v[10:11], v[190:191], v[254:255]
	v_add_f32_dpp v14, v14, v14 quad_perm:[2,3,0,1] row_mask:0xf bank_mask:0xf bound_ctrl:1
	v_pk_mul_f32 v[12:13], v[8:9], v[244:245]
	v_pk_fma_f32 v[12:13], v[10:11], v[246:247], v[12:13]
	v_add_f32_dpp v14, v14, v14 row_half_mirror row_mask:0xf bank_mask:0xf bound_ctrl:1
	v_add_f32_e32 v32, v12, v13
	s_nop 0
	v_add_f32_dpp v14, v14, v14 row_mirror row_mask:0xf bank_mask:0xf bound_ctrl:1
	v_pk_fma_f32 v[10:11], v[14:15], v[194:195], v[254:255] op_sel_hi:[0,1,1]
	v_pk_fma_f32 v[8:9], v[14:15], v[192:193], v[252:253] op_sel_hi:[0,1,1]
	v_pk_mul_f32 v[12:13], v[8:9], v[200:201]
	v_add_f32_dpp v34, v18, v18 row_mirror row_mask:0xf bank_mask:0x3 bound_ctrl:1
	v_pk_fma_f32 v[12:13], v[10:11], v[202:203], v[12:13]
	v_add_f32_dpp v35, v19, v19 row_mirror row_mask:0xf bank_mask:0x3 bound_ctrl:1
	v_add_f32_dpp v36, v20, v20 row_mirror row_mask:0xf bank_mask:0x3 bound_ctrl:1
	v_add_f32_e32 v33, v12, v13
	v_add_f32_dpp v37, v21, v21 row_mirror row_mask:0xf bank_mask:0x3 bound_ctrl:1
	v_add_f32_dpp v38, v22, v22 row_mirror row_mask:0xf bank_mask:0x3 bound_ctrl:1
	v_add_f32_dpp v39, v23, v23 row_mirror row_mask:0xf bank_mask:0x3 bound_ctrl:1
	v_add_f32_dpp v40, v24, v24 row_mirror row_mask:0xf bank_mask:0x3 bound_ctrl:1
	v_add_f32_dpp v41, v25, v25 row_mirror row_mask:0xf bank_mask:0x3 bound_ctrl:1
	v_add_f32_dpp v34, v26, v26 row_mirror row_mask:0xf bank_mask:0xc bound_ctrl:1
	v_add_f32_dpp v35, v27, v27 row_mirror row_mask:0xf bank_mask:0xc bound_ctrl:1
	v_add_f32_dpp v36, v28, v28 row_mirror row_mask:0xf bank_mask:0xc bound_ctrl:1
	v_add_f32_dpp v37, v29, v29 row_mirror row_mask:0xf bank_mask:0xc bound_ctrl:1
	v_add_f32_dpp v38, v30, v30 row_mirror row_mask:0xf bank_mask:0xc bound_ctrl:1
	v_add_f32_dpp v39, v31, v31 row_mirror row_mask:0xf bank_mask:0xc bound_ctrl:1
	v_add_f32_dpp v40, v32, v32 row_mirror row_mask:0xf bank_mask:0xc bound_ctrl:1
	v_add_f32_dpp v41, v33, v33 row_mirror row_mask:0xf bank_mask:0xc bound_ctrl:1
	v_add_f32_dpp v42, v34, v34 row_half_mirror row_mask:0xf bank_mask:0x5 bound_ctrl:1
	v_add_f32_dpp v43, v35, v35 row_half_mirror row_mask:0xf bank_mask:0x5 bound_ctrl:1
	v_add_f32_dpp v44, v36, v36 row_half_mirror row_mask:0xf bank_mask:0x5 bound_ctrl:1
	v_add_f32_dpp v45, v37, v37 row_half_mirror row_mask:0xf bank_mask:0x5 bound_ctrl:1
	v_add_f32_dpp v42, v38, v38 row_half_mirror row_mask:0xf bank_mask:0xa bound_ctrl:1
	v_add_f32_dpp v43, v39, v39 row_half_mirror row_mask:0xf bank_mask:0xa bound_ctrl:1
	v_add_f32_dpp v44, v40, v40 row_half_mirror row_mask:0xf bank_mask:0xa bound_ctrl:1
	v_add_f32_dpp v45, v41, v41 row_half_mirror row_mask:0xf bank_mask:0xa bound_ctrl:1
	v_cndmask_b32_e64 v80, v44, v42, s[42:43]
	v_cndmask_b32_e64 v121, v42, v44, s[42:43]
	v_cndmask_b32_e64 v82, v45, v43, s[42:43]
	v_cndmask_b32_e64 v122, v43, v45, s[42:43]
	v_lshl_add_u32 v16, v100, 11, v99
	v_add_u32_e32 v100, v132, v100
	v_add_f32_dpp v13, v121, v80 quad_perm:[2,3,0,1] row_mask:0xf bank_mask:0xf bound_ctrl:1
	v_add_f32_dpp v14, v122, v82 quad_perm:[2,3,0,1] row_mask:0xf bank_mask:0xf bound_ctrl:1
	v_cndmask_b32_e64 v12, v13, v14, s[44:45]
	v_cndmask_b32_e64 v13, v14, v13, s[44:45]
	s_add_i32 s6, s6, 16
	s_cmp_eq_u32 s10, 15
	v_add_f32_dpp v13, v12, v13 quad_perm:[1,0,3,2] row_mask:0xf bank_mask:0xf bound_ctrl:1
	s_cbranch_scc0 .Lscan_tail_nox
	v_mov_b32_e32 v100, v101
.Lscan_tail_nox:
	v_cvt_pk_bf16_f32 v14, v13, v13
	global_store_short v16, v14, s[100:101]
	s_add_i32 s10, s10, 1
	s_cmpk_eq_i32 s6, 0x20f0
	s_waitcnt lgkmcnt(0)
	s_barrier
	s_cbranch_scc1 .LBB0_767
	s_branch .LBB0_774
